# rw_chunk_prep: previous-token rows, per-channel params and all four tokens' rows of a group now share one memory round trip
# baseline (speedup 1.0000x reference)
; #define LAS __attribute__((address_space(3)))
; __device__ __forceinline__ f32x4 bf4(v2u u) { return (f32x4){bflo(u.x), bfhi(u.x), bflo(u.y), bfhi(u.y)}; }
; #define MFMA32(a, b, c) __builtin_amdgcn_mfma_f32_16x16x32_bf16(a, b, c, 0, 0, 0)
; __device__ __forceinline__ void rw_chunk_prep(const Args& a, int head, int tc0, const LAS bf16* TDr, const LAS bf16* DAr, LAS unsigned char* lw_, int lane) {
;     ...
;     {   bf16x8 atd[2], ada[2];
; #pragma unroll
;         for (int kk = 0; kk < 2; ++kk) { atd[kk] = *(const LAS bf16x8*)(TDr + j * 64 + kk * 32 + kg * 8); ada[kk] = *(const LAS bf16x8*)(DAr + j * 64 + kk * 32 + kg * 8); }
; #pragma unroll
;         for (int cb = 0; cb < 4; ++cb) { accw[cb] = (f32x4){0.f, 0.f, 0.f, 0.f}; acca[cb] = (f32x4){0.f, 0.f, 0.f, 0.f};
; #pragma unroll
;             for (int kk = 0; kk < 2; ++kk) { const bf16x8 bw = *(const bf16x8*)(W2t + (size_t)(cbase + cb) * 64 + kk * 32 + kg * 8), ba = *(const bf16x8*)(A2t + (size_t)(cbase + cb) * 64 + kk * 32 + kg * 8);
;                 accw[cb] = MFMA32(atd[kk], bw, accw[cb]); acca[cb] = MFMA32(ada[kk], ba, acca[cb]); } }
;     }
;     const f32x4 w0 = ld4(a.in[9] + cbase), a0 = ld4(a.in[11] + cbase), kkw = ld4(a.in[13] + cbase), kaw = ld4(a.in[14] + cbase), rkw = ld4(a.in[15] + cbase);
;     const f32x4 mur = ld4(a.in[4] + cbase), muk = ld4(a.in[5] + cbase), muv = ld4(a.in[6] + cbase);
;     float* RK = (float*)(ws + WS_RK);
;     f32x4 rr[4], km[4], av[4], bv[4], lw[4], vv[4];
;     {   const int tt0 = tc0 + 4 * rg; const f32x4 zero = {0.f, 0.f, 0.f, 0.f};
;         f32x4 pr = tt0 > 0 ? bf4(*(const v2u*)(ZA + (size_t)(tt0 - 1) * 3072 + cbase)) : zero;
;         f32x4 pk = tt0 > 0 ? bf4(*(const v2u*)(ZA + (size_t)(tt0 - 1) * 3072 + 1024 + cbase)) : zero;
;         f32x4 pv = tt0 > 0 ? bf4(*(const v2u*)(ZA + (size_t)(tt0 - 1) * 3072 + 2048 + cbase)) : zero;
; #pragma unroll
;         for (int i = 0; i < 4; ++i) {
;             const int tt = tt0 + i;
;             const f32x4 zr = bf4(*(const v2u*)(ZA + (size_t)tt * 3072 + cbase)), zk = bf4(*(const v2u*)(ZA + (size_t)tt * 3072 + 1024 + cbase)), zv = bf4(*(const v2u*)(ZA + (size_t)tt * 3072 + 2048 + cbase));
.LBB0_329:
	s_lshr_b32 s0, s59, 1
	s_add_i32 s0, s0, s34
	s_and_b32 s2, s58, 16
	v_lshl_add_u32 v4, s2, 7, v155
	v_lshl_or_b32 v66, s0, 6, v154
	ds_read_b128 v[0:3], v4
	ds_read_b128 v[16:19], v4 offset:4096
	ds_read_b128 v[20:23], v4 offset:64
	ds_read_b128 v[36:39], v4 offset:4160
	v_lshlrev_b64 v[4:5], 7, v[66:67]
	v_lshl_add_u64 v[12:13], v[74:75], 0, v[4:5]
	v_lshl_add_u64 v[24:25], v[76:77], 0, v[4:5]
	global_load_dwordx4 v[4:7], v[12:13], off
	global_load_dwordx4 v[8:11], v[24:25], off
	global_load_dwordx4 v[12:15], v[12:13], off offset:64
	global_load_dwordx4 v[24:27], v[24:25], off offset:64
	v_or_b32_e32 v214, 1, v66
	v_mov_b32_e32 v215, v67
	v_lshlrev_b64 v[214:215], 7, v[214:215]
	v_lshl_add_u64 v[218:219], v[76:77], 0, v[214:215]
	v_lshl_add_u64 v[214:215], v[74:75], 0, v[214:215]
	global_load_dwordx4 v[206:209], v[214:215], off
	global_load_dwordx4 v[210:213], v[218:219], off
	global_load_dwordx4 v[214:217], v[214:215], off offset:64
	global_load_dwordx4 v[218:221], v[218:219], off offset:64
	v_or_b32_e32 v230, 2, v66
	v_mov_b32_e32 v231, v67
	v_lshlrev_b64 v[230:231], 7, v[230:231]
	v_lshl_add_u64 v[234:235], v[76:77], 0, v[230:231]
	v_lshl_add_u64 v[230:231], v[74:75], 0, v[230:231]
	global_load_dwordx4 v[222:225], v[230:231], off
	global_load_dwordx4 v[226:229], v[234:235], off
	global_load_dwordx4 v[230:233], v[230:231], off offset:64
	global_load_dwordx4 v[234:237], v[234:235], off offset:64
	v_or_b32_e32 v246, 3, v66
	v_mov_b32_e32 v247, v67
	v_lshlrev_b64 v[246:247], 7, v[246:247]
	v_lshl_add_u64 v[250:251], v[76:77], 0, v[246:247]
	v_lshl_add_u64 v[246:247], v[74:75], 0, v[246:247]
	global_load_dwordx4 v[238:241], v[246:247], off
	global_load_dwordx4 v[242:245], v[250:251], off
	global_load_dwordx4 v[246:249], v[246:247], off offset:64
	global_load_dwordx4 v[250:253], v[250:251], off offset:64
	s_or_b32 s60, s2, s57
	v_add_u32_e32 v106, s60, v157
	v_cmp_lt_i32_e32 vcc, 0, v106
	v_mov_b32_e32 v186, 0
	v_add_u32_e32 v96, -1, v106
	v_mov_b32_e32 v98, 0
	v_mov_b32_e32 v100, 0
	v_mov_b32_e32 v99, 0
	v_mov_b32_e32 v101, 0
	s_waitcnt vmcnt(15) lgkmcnt(3)
	v_mfma_f32_16x16x32_bf16 v[4:7], v[0:3], v[4:7], 0
	s_waitcnt vmcnt(14) lgkmcnt(2)
	v_mfma_f32_16x16x32_bf16 v[8:11], v[16:19], v[8:11], 0
	s_waitcnt vmcnt(12) lgkmcnt(0)
	v_mfma_f32_16x16x32_bf16 v[24:27], v[36:39], v[24:27], v[8:11]
	v_mfma_f32_16x16x32_bf16 v[4:7], v[20:23], v[12:15], v[4:7]
	s_nop 4
	s_waitcnt vmcnt(11)
	v_mfma_f32_16x16x32_bf16 v[8:11], v[0:3], v[206:209], 0
	s_waitcnt vmcnt(10)
	v_mfma_f32_16x16x32_bf16 v[12:15], v[16:19], v[210:213], 0
	s_waitcnt vmcnt(9)
	v_mfma_f32_16x16x32_bf16 v[8:11], v[20:23], v[214:217], v[8:11]
	s_waitcnt vmcnt(8)
	v_mfma_f32_16x16x32_bf16 v[28:31], v[36:39], v[218:221], v[12:15]
	s_nop 3
	s_waitcnt vmcnt(7)
	v_mfma_f32_16x16x32_bf16 v[12:15], v[0:3], v[222:225], 0
	s_waitcnt vmcnt(6)
	v_mfma_f32_16x16x32_bf16 v[32:35], v[16:19], v[226:229], 0
	s_waitcnt vmcnt(5)
	v_mfma_f32_16x16x32_bf16 v[12:15], v[20:23], v[230:233], v[12:15]
	s_waitcnt vmcnt(4)
	v_mfma_f32_16x16x32_bf16 v[32:35], v[36:39], v[234:237], v[32:35]
	s_waitcnt vmcnt(3)
	v_mfma_f32_16x16x32_bf16 v[0:3], v[0:3], v[238:241], 0
	s_waitcnt vmcnt(2)
	v_mfma_f32_16x16x32_bf16 v[40:43], v[16:19], v[242:245], 0
	s_waitcnt vmcnt(1)
	v_mfma_f32_16x16x32_bf16 v[16:19], v[20:23], v[246:249], v[0:3]
	s_nop 2
	v_lshlrev_b64 v[0:1], 2, v[66:67]
	v_lshl_add_u64 v[2:3], s[38:39], 0, v[0:1]
	global_load_dwordx4 v[20:23], v[2:3], off
	v_lshl_add_u64 v[2:3], s[42:43], 0, v[0:1]
	global_load_dwordx4 v[60:63], v[2:3], off
	v_lshl_add_u64 v[2:3], s[46:47], 0, v[0:1]
	s_waitcnt vmcnt(2)
	v_mfma_f32_16x16x32_bf16 v[56:59], v[36:39], v[250:253], v[40:43]
	global_load_dwordx4 v[36:39], v[2:3], off
	v_lshl_add_u64 v[2:3], s[48:49], 0, v[0:1]
	global_load_dwordx4 v[52:55], v[2:3], off
	v_lshl_add_u64 v[2:3], s[50:51], 0, v[0:1]
	global_load_dwordx4 v[40:43], v[2:3], off
	v_lshl_add_u64 v[2:3], s[76:77], 0, v[0:1]
	global_load_dwordx4 v[44:47], v[2:3], off
	v_lshl_add_u64 v[2:3], s[78:79], 0, v[0:1]
	v_lshl_add_u64 v[0:1], s[80:81], 0, v[0:1]
	global_load_dwordx4 v[48:51], v[2:3], off
	v_lshlrev_b32_e32 v66, 1, v66
	global_load_dwordx4 v[0:3], v[0:1], off
	v_mov_b32_e32 v102, 0
	v_mov_b32_e32 v103, 0
	v_mov_b32_e32 v104, 0
	v_mov_b32_e32 v105, 0
	v_mov_b32_e32 v188, 0
	v_mov_b32_e32 v187, 0
	v_mov_b32_e32 v189, 0
	v_mov_b32_e32 v230, s45
	v_mov_b32_e32 v231, 0
	v_mov_b32_e32 v242, 0x1000
	v_mov_b32_e32 v243, 0
	s_and_saveexec_b64 s[100:101], vcc
	v_mov_b64_e32 v[108:109], s[72:73]
	v_mad_u64_u32 v[108:109], s[26:27], v96, s44, v[108:109]
	v_lshl_add_u64 v[108:109], v[108:109], 0, v[66:67]
	v_lshl_add_u64 v[244:245], v[108:109], 0, v[242:243]
	global_load_dwordx2 v[100:101], v[108:109], off
	global_load_dwordx2 v[104:105], v[108:109], off offset:2048
	global_load_dwordx2 v[246:247], v[244:245], off
	s_or_b64 exec, exec, s[100:101]
	v_mov_b64_e32 v[96:97], s[72:73]
	v_mad_i64_i32 v[96:97], s[2:3], v106, s44, v[96:97]
	v_lshl_add_u64 v[96:97], v[96:97], 0, v[66:67]
	v_lshl_add_u64 v[248:249], v[96:97], 0, v[230:231]
	global_load_dwordx2 v[108:109], v[96:97], off
	global_load_dwordx2 v[110:111], v[96:97], off offset:2048
	global_load_dwordx2 v[96:97], v[248:249], off
	v_or_b32_e32 v224, 1, v106
	v_mov_b64_e32 v[226:227], s[72:73]
	v_mad_i64_i32 v[226:227], s[2:3], v224, s44, v[226:227]
	v_lshl_add_u64 v[226:227], v[226:227], 0, v[66:67]
	v_lshl_add_u64 v[228:229], v[226:227], 0, v[230:231]
	global_load_dwordx2 v[206:207], v[226:227], off
	global_load_dwordx2 v[208:209], v[226:227], off offset:2048
	global_load_dwordx2 v[210:211], v[228:229], off
	v_or_b32_e32 v224, 2, v106
	v_mov_b64_e32 v[232:233], s[72:73]
	v_mad_i64_i32 v[232:233], s[2:3], v224, s44, v[232:233]
	v_lshl_add_u64 v[232:233], v[232:233], 0, v[66:67]
	v_lshl_add_u64 v[234:235], v[232:233], 0, v[230:231]
	global_load_dwordx2 v[212:213], v[232:233], off
	global_load_dwordx2 v[214:215], v[232:233], off offset:2048
	global_load_dwordx2 v[216:217], v[234:235], off
	v_or_b32_e32 v224, 3, v106
	v_mov_b64_e32 v[238:239], s[72:73]
	v_mad_i64_i32 v[238:239], s[2:3], v224, s44, v[238:239]
	v_lshl_add_u64 v[238:239], v[238:239], 0, v[66:67]
	v_lshl_add_u64 v[240:241], v[238:239], 0, v[230:231]
	global_load_dwordx2 v[218:219], v[238:239], off
	global_load_dwordx2 v[220:221], v[238:239], off offset:2048
	global_load_dwordx2 v[222:223], v[240:241], off
	s_waitcnt vmcnt(12)
	s_and_saveexec_b64 s[100:101], vcc
	v_lshlrev_b32_e32 v98, 16, v100
	v_and_b32_e32 v100, 0xffff0000, v100
	v_lshlrev_b32_e32 v99, 16, v101
	v_and_b32_e32 v101, 0xffff0000, v101
	v_lshlrev_b32_e32 v102, 16, v104
	v_and_b32_e32 v103, 0xffff0000, v104
	v_lshlrev_b32_e32 v104, 16, v105
	v_and_b32_e32 v105, 0xffff0000, v105
	v_lshlrev_b32_e32 v186, 16, v246
	v_and_b32_e32 v188, 0xffff0000, v246
	v_lshlrev_b32_e32 v187, 16, v247
	v_and_b32_e32 v189, 0xffff0000, v247
	s_or_b64 exec, exec, s[100:101]
; __device__ __forceinline__ f32x4 bf4(v2u u) { return (f32x4){bflo(u.x), bfhi(u.x), bflo(u.y), bfhi(u.y)}; }
; __device__ __forceinline__ void rw_chunk_prep(const Args& a, int head, int tc0, const LAS bf16* TDr, const LAS bf16* DAr, LAS unsigned char* lw_, int lane) {
;     ...
;             const f32x4 zr = bf4(*(const v2u*)(ZA + (size_t)tt * 3072 + cbase)), zk = bf4(*(const v2u*)(ZA + (size_t)tt * 3072 + 1024 + cbase)), zv = bf4(*(const v2u*)(ZA + (size_t)tt * 3072 + 2048 + cbase));
;             const f32x4 r = zr + (pr - zr) * mur, k = zk + (pk - zk) * muk, v = zv + (pv - zv) * muv;
;             pr = zr; pk = zk; pv = zv;
;             f32x4 lwv, alr;
; #pragma unroll
;             for (int cb = 0; cb < 4; ++cb) { const float x = -(w0[cb] + accw[cb][i]); const float sp = fmaxf(x, 0.f) + __logf(1.f + __expf(-fabsf(x))); lwv[cb] = -__expf(-sp - 0.5f); alr[cb] = __builtin_amdgcn_rcpf(1.f + __expf(-(a0[cb] + acca[cb][i]))); }
;             const f32x4 kkr = k * kkw, kmod = k * (1.f + (alr - 1.f) * kaw);
;             float ssq = (kkr.x * kkr.x + kkr.y * kkr.y) + (kkr.z * kkr.z + kkr.w * kkr.w);
;             const f32x4 rkk = r * kmod * rkw; float rkp = (rkk.x + rkk.y) + (rkk.z + rkk.w);
;             ssq = row16_sum(ssq); rkp = row16_sum(rkp);
;             const float inv = __builtin_amdgcn_rsqf(fmaxf(ssq, 1e-24f));
;             const f32x4 kk = kkr * inv;
;             rr[i] = r; km[i] = kmod; av[i] = -kk; bv[i] = kk * alr; lw[i] = lwv; vv[i] = v;
;             if (j == 0) RK[(size_t)tt * 16 + head] = rkp;
.LBB0_335:
	v_add_f32_e32 v107, v24, v60
	v_add_f32_e32 v28, v28, v61
	v_add_f32_e32 v32, v32, v62
	v_add_f32_e32 v56, v56, v63
	v_mul_f32_e32 v107, 0xbfb8aa3b, v107
	v_mul_f32_e32 v28, 0xbfb8aa3b, v28
	v_mul_f32_e32 v32, 0xbfb8aa3b, v32
	v_mul_f32_e32 v56, 0xbfb8aa3b, v56
	v_exp_f32_e32 v107, v107
	v_exp_f32_e32 v28, v28
	v_exp_f32_e32 v32, v32
	v_exp_f32_e32 v56, v56
	v_add_f32_e32 v107, 1.0, v107
	v_add_f32_e32 v28, 1.0, v28
	v_add_f32_e32 v32, 1.0, v32
	v_add_f32_e32 v56, 1.0, v56
	v_rcp_f32_e32 v112, v107
	v_rcp_f32_e32 v114, v32
	v_rcp_f32_e32 v115, v56
	v_rcp_f32_e32 v113, v28
	s_lshl_b64 s[2:3], s[0:1], 2
	v_mov_b32_e32 v190, v67
	v_pk_add_f32 v[116:117], v[114:115], -1.0 op_sel_hi:[1,0]
	v_pk_add_f32 v[118:119], v[112:113], -1.0 op_sel_hi:[1,0]
	s_waitcnt vmcnt(16)
	v_pk_fma_f32 v[130:131], v[54:55], v[116:117], 1.0 op_sel_hi:[1,1,0]
	v_pk_fma_f32 v[128:129], v[52:53], v[118:119], 1.0 op_sel_hi:[1,1,0]
	v_mov_b32_e32 v24, v67
	s_add_u32 s26, s35, s2
	s_addc_u32 s27, s36, s3
	s_waitcnt vmcnt(11)
	v_lshlrev_b32_e32 v122, 16, v108
	v_and_b32_e32 v123, 0xffff0000, v108
	v_lshlrev_b32_e32 v124, 16, v109
	s_waitcnt vmcnt(10)
	v_lshlrev_b32_e32 v120, 16, v110
	v_and_b32_e32 v121, 0xffff0000, v110
	v_lshlrev_b32_e32 v126, 16, v111
	v_and_b32_e32 v127, 0xffff0000, v111
	v_and_b32_e32 v125, 0xffff0000, v109
	v_sub_f32_e32 v109, v100, v123
	v_sub_f32_e32 v108, v98, v122
	v_sub_f32_e32 v100, v99, v124
	v_sub_f32_e32 v99, v105, v127
	v_sub_f32_e32 v98, v104, v126
	v_sub_f32_e32 v103, v103, v121
	v_sub_f32_e32 v102, v102, v120
	v_sub_f32_e32 v101, v101, v125
	v_pk_fma_f32 v[102:103], v[48:49], v[102:103], v[120:121]
	v_pk_fma_f32 v[98:99], v[50:51], v[98:99], v[126:127]
	v_pk_fma_f32 v[110:111], v[46:47], v[100:101], v[124:125]
	v_pk_fma_f32 v[108:109], v[44:45], v[108:109], v[122:123]
	v_pk_mul_f32 v[118:119], v[38:39], v[98:99]
	v_pk_mul_f32 v[116:117], v[36:37], v[102:103]
	v_pk_mul_f32 v[100:101], v[130:131], v[98:99]
	v_pk_mul_f32 v[102:103], v[128:129], v[102:103]
	v_pk_mul_f32 v[98:99], v[118:119], v[118:119]
	v_pk_mul_f32 v[104:105], v[116:117], v[116:117]
	v_pk_mul_f32 v[128:129], v[108:109], v[102:103]
	v_pk_mul_f32 v[130:131], v[110:111], v[100:101]
	v_pk_mov_b32 v[132:133], v[104:105], v[98:99] op_sel:[1,0]
	v_mov_b32_e32 v105, v99
	v_pk_mul_f32 v[98:99], v[42:43], v[130:131]
	v_pk_mul_f32 v[128:129], v[40:41], v[128:129]
	v_pk_add_f32 v[104:105], v[132:133], v[104:105]
	v_add_f32_e32 v28, v128, v129
	v_add_f32_e32 v32, v98, v99
	v_add_f32_e32 v56, v104, v105
	v_add_f32_e32 v28, v28, v32
	s_nop 0
	v_add_f32_dpp v32, v56, v56 quad_perm:[1,0,3,2] row_mask:0xf bank_mask:0xf bound_ctrl:1
	v_add_f32_dpp v28, v28, v28 quad_perm:[1,0,3,2] row_mask:0xf bank_mask:0xf bound_ctrl:1
	s_nop 0
	v_add_f32_dpp v32, v32, v32 quad_perm:[2,3,0,1] row_mask:0xf bank_mask:0xf bound_ctrl:1
	v_add_f32_dpp v28, v28, v28 quad_perm:[2,3,0,1] row_mask:0xf bank_mask:0xf bound_ctrl:1
	s_nop 0
	v_add_f32_dpp v191, v32, v32 row_half_mirror row_mask:0xf bank_mask:0xf bound_ctrl:1
	v_add_f32_dpp v28, v28, v28 row_half_mirror row_mask:0xf bank_mask:0xf bound_ctrl:1
	s_nop 0
	v_mov_b32_dpp v190, v191 row_mirror row_mask:0xf bank_mask:0xf
	v_mov_b32_dpp v24, v28 row_mirror row_mask:0xf bank_mask:0xf
	s_and_saveexec_b64 s[2:3], s[24:25]
	s_cbranch_execz .LBB0_337
	v_ashrrev_i32_e32 v107, 31, v106
	v_lshlrev_b64 v[98:99], 6, v[106:107]
	v_lshl_add_u64 v[98:99], s[26:27], 0, v[98:99]
	v_add_f32_e32 v24, v28, v24
	global_store_dword v[98:99], v24, off
